# plus GEMM2 epilogue: eight g_c gate loads issued up front, counted waits, no vmcnt(0) after each load
# baseline (speedup 1.0000x reference)
;     __device__ __forceinline__ bf16_t* G() const { return (bf16_t*)(ws + OFF_G); }
;     __device__ __forceinline__ bf16_t* Mb() const { return (bf16_t*)(ws + OFF_MB); }
; __device__ __forceinline__ unsigned pk2(float lo, float hi) { const f32x2_t f = {lo, hi}; const bf16x2_t b = __builtin_convertvector(f, bf16x2_t); return __builtin_bit_cast(unsigned, b); }
; __device__ __forceinline__ int opaque_tid() { int t = threadIdx.x; asm volatile("" : "+v"(t)); return t; }
; #define LAS __attribute__((address_space(3)))
; __device__ __forceinline__ float ub(unsigned w, int j) { return (float)((w >> (8 * j)) & 0xffu); }
; template <bool PERMF = false, class F>
; __device__ __forceinline__ void epi_store_rows(LAS unsigned char* lds, int wid, int lane2, int fr, int fq, int wc, int mt, bf16_t* dbase, size_t dld, F getpk) {
;     ...
; #pragma unroll
;     for (int bj = 0; bj < 2; bj++)
; #pragma unroll
;         for (int n = 0; n < 2; n++)
; #pragma unroll
;             for (int m = 0; m < 4; m++) *(LAS u32x2*)(reg + ((bj * 2 + n) * 16 + fr) * LROW + (PERMF ? fq * 32 + m * 8 : fq * 8 + m * 32)) = getpk(bj, n, m);
; __device__ __forceinline__ void phase_gemm2(const Params& p, int layer, LAS unsigned char* lds) {
;     ...
;         const int tid2 = opaque_tid(), lane2 = tid2 & 63, fr = lane2 & 15, fq = lane2 >> 4;
; #pragma unroll
;         for (int ai = 0; ai < 2; ai++) {
;             const int f0 = nt * 256 + ai * 128 + wr * 64;
;             epi_store_rows<true>(lds, wid, lane2, fr, fq, wc, mt, p.Mb() + f0, DM, [&](int bj, int n, int m) -> u32x2 {
;                 const int tk = mt * 256 + bj * 128 + wc * 32 + n * 16 + fr;
;                 const unsigned gw = *(const unsigned*)((const unsigned char*)p.G() + (size_t)tk * 3072 + 2048 + f0 + fq * 16 + m * 4);
;                 const f32x4 v = acc[ai][bj][m][n] * (1.f / 255.f);
;                 return (u32x2){pk2(v[0] * ub(gw, 0), v[1] * ub(gw, 1)), pk2(v[2] * ub(gw, 2), v[3] * ub(gw, 3))};
.LBB0_578:
	v_mov_b32_e32 v130, v168
	s_or_b32 s0, s0, s40
	v_and_b32_e32 v0, 15, v130
	v_lshlrev_b32_e32 v131, 1, v130
	v_and_b32_e32 v131, 0x60, v131
	v_mul_u32_u24_e32 v132, 0x90, v0
	v_add3_u32 v155, s42, v131, v132
	v_lshlrev_b32_e32 v131, 4, v130
	v_bfe_u32 v132, v130, 3, 3
	v_or_b32_e32 v138, s0, v0
	v_and_b32_e32 v0, 48, v130
	v_and_b32_e32 v148, 0x70, v131
	v_mul_u32_u24_e32 v130, 0x90, v132
	v_add3_u32 v154, s42, v148, v130
	v_or_b32_e32 v130, s0, v132
	v_ashrrev_i32_e32 v131, 31, v130
	v_or_b32_e32 v133, 8, v132
	v_lshlrev_b64 v[146:147], 11, v[130:131]
	v_or_b32_e32 v130, s0, v133
	v_ashrrev_i32_e32 v131, 31, v130
	v_or_b32_e32 v139, 16, v132
	v_lshlrev_b64 v[144:145], 11, v[130:131]
	v_or_b32_e32 v130, s0, v139
	v_ashrrev_i32_e32 v131, 31, v130
	v_or_b32_e32 v150, 24, v132
	v_lshlrev_b64 v[142:143], 11, v[130:131]
	v_or_b32_e32 v130, s0, v150
	v_ashrrev_i32_e32 v131, 31, v130
	s_bitset1_b32 s0, 7
	v_lshlrev_b64 v[140:141], 11, v[130:131]
	v_or_b32_e32 v130, s0, v132
	v_ashrrev_i32_e32 v131, 31, v130
	v_lshlrev_b64 v[136:137], 11, v[130:131]
	v_or_b32_e32 v130, s0, v133
	s_add_i32 s4, s67, s3
	v_ashrrev_i32_e32 v131, 31, v130
	v_mov_b64_e32 v[152:153], s[20:21]
	v_or_b32_e32 v157, 16, v138
	v_or_b32_e32 v156, 0x80, v138
	v_or_b32_e32 v149, 0x90, v138
	v_lshlrev_b64 v[134:135], 11, v[130:131]
	v_or_b32_e32 v130, s0, v139
	s_ashr_i32 s5, s4, 31
	v_mad_i64_i32 v[138:139], s[6:7], v138, s90, v[152:153]
	v_lshl_add_u64 v[138:139], v[138:139], 0, s[4:5]
	v_ashrrev_i32_e32 v131, 31, v130
	v_lshl_add_u64 v[138:139], v[138:139], 0, v[0:1]
	s_mov_b64 s[8:9], 0x17e3e900
	v_lshlrev_b64 v[132:133], 11, v[130:131]
	v_or_b32_e32 v130, s0, v150
	v_lshl_add_u64 v[150:151], v[138:139], 0, s[8:9]
	v_add_co_u32_e32 v138, vcc, s81, v138
	v_pk_mul_f32 v[126:127], v[126:127], s[2:3] op_sel_hi:[1,0]
	s_nop 0
	v_addc_co_u32_e32 v139, vcc, 0, v139, vcc
	global_load_dwordx4 v[192:195], v[150:151], off
	global_load_dwordx4 v[196:199], v[150:151], off offset:128
	v_mad_i64_i32 v[162:163], s[6:7], v157, s90, v[152:153]
	v_lshl_add_u64 v[162:163], v[162:163], 0, s[4:5]
	v_lshl_add_u64 v[162:163], v[162:163], 0, v[0:1]
	v_lshl_add_u64 v[162:163], v[162:163], 0, s[8:9]
	global_load_dwordx4 v[200:203], v[162:163], off
	global_load_dwordx4 v[204:207], v[162:163], off offset:128
	v_mad_i64_i32 v[162:163], s[6:7], v156, s90, v[152:153]
	v_lshl_add_u64 v[162:163], v[162:163], 0, s[4:5]
	v_lshl_add_u64 v[162:163], v[162:163], 0, v[0:1]
	v_lshl_add_u64 v[162:163], v[162:163], 0, s[8:9]
	global_load_dwordx4 v[208:211], v[162:163], off
	global_load_dwordx4 v[212:215], v[162:163], off offset:128
	v_mad_i64_i32 v[162:163], s[6:7], v149, s90, v[152:153]
	v_lshl_add_u64 v[162:163], v[162:163], 0, s[4:5]
	v_lshl_add_u64 v[162:163], v[162:163], 0, v[0:1]
	v_lshl_add_u64 v[162:163], v[162:163], 0, s[8:9]
	global_load_dwordx4 v[216:219], v[162:163], off
	global_load_dwordx4 v[220:223], v[162:163], off offset:128
	v_pk_mul_f32 v[128:129], v[128:129], s[2:3] op_sel_hi:[1,0]
	v_pk_mul_f32 v[122:123], v[122:123], s[2:3] op_sel_hi:[1,0]
	v_pk_mul_f32 v[124:125], v[124:125], s[2:3] op_sel_hi:[1,0]
	v_pk_mul_f32 v[118:119], v[118:119], s[2:3] op_sel_hi:[1,0]
	v_pk_mul_f32 v[120:121], v[120:121], s[2:3] op_sel_hi:[1,0]
	v_pk_mul_f32 v[114:115], v[114:115], s[2:3] op_sel_hi:[1,0]
	v_pk_mul_f32 v[116:117], v[116:117], s[2:3] op_sel_hi:[1,0]
	v_pk_mul_f32 v[110:111], v[110:111], s[2:3] op_sel_hi:[1,0]
	v_pk_mul_f32 v[112:113], v[112:113], s[2:3] op_sel_hi:[1,0]
	v_pk_mul_f32 v[106:107], v[106:107], s[2:3] op_sel_hi:[1,0]
	v_pk_mul_f32 v[108:109], v[108:109], s[2:3] op_sel_hi:[1,0]
	v_pk_mul_f32 v[102:103], v[102:103], s[2:3] op_sel_hi:[1,0]
	v_pk_mul_f32 v[104:105], v[104:105], s[2:3] op_sel_hi:[1,0]
	v_pk_mul_f32 v[98:99], v[98:99], s[2:3] op_sel_hi:[1,0]
	v_pk_mul_f32 v[100:101], v[100:101], s[2:3] op_sel_hi:[1,0]
	v_pk_mul_f32 v[94:95], v[94:95], s[2:3] op_sel_hi:[1,0]
	v_pk_mul_f32 v[96:97], v[96:97], s[2:3] op_sel_hi:[1,0]
	v_pk_mul_f32 v[90:91], v[90:91], s[2:3] op_sel_hi:[1,0]
	v_pk_mul_f32 v[92:93], v[92:93], s[2:3] op_sel_hi:[1,0]
	v_pk_mul_f32 v[86:87], v[86:87], s[2:3] op_sel_hi:[1,0]
	v_pk_mul_f32 v[88:89], v[88:89], s[2:3] op_sel_hi:[1,0]
	v_pk_mul_f32 v[82:83], v[82:83], s[2:3] op_sel_hi:[1,0]
	v_pk_mul_f32 v[84:85], v[84:85], s[2:3] op_sel_hi:[1,0]
	v_pk_mul_f32 v[78:79], v[78:79], s[2:3] op_sel_hi:[1,0]
	v_pk_mul_f32 v[80:81], v[80:81], s[2:3] op_sel_hi:[1,0]
	v_pk_mul_f32 v[74:75], v[74:75], s[2:3] op_sel_hi:[1,0]
	v_pk_mul_f32 v[76:77], v[76:77], s[2:3] op_sel_hi:[1,0]
	v_pk_mul_f32 v[70:71], v[70:71], s[2:3] op_sel_hi:[1,0]
	v_pk_mul_f32 v[72:73], v[72:73], s[2:3] op_sel_hi:[1,0]
	v_pk_mul_f32 v[66:67], v[66:67], s[2:3] op_sel_hi:[1,0]
	v_pk_mul_f32 v[68:69], v[68:69], s[2:3] op_sel_hi:[1,0]
	s_lshl_b64 s[0:1], s[4:5], 1
	s_add_u32 s0, s60, s0
	s_addc_u32 s1, s61, s1
	v_ashrrev_i32_e32 v131, 31, v130
	v_lshlrev_b64 v[130:131], 11, v[130:131]
	v_pk_mul_f32 v[62:63], v[62:63], s[2:3] op_sel_hi:[1,0]
	v_pk_mul_f32 v[64:65], v[64:65], s[2:3] op_sel_hi:[1,0]
	v_pk_mul_f32 v[58:59], v[58:59], s[2:3] op_sel_hi:[1,0]
	v_pk_mul_f32 v[60:61], v[60:61], s[2:3] op_sel_hi:[1,0]
	v_pk_mul_f32 v[54:55], v[54:55], s[2:3] op_sel_hi:[1,0]
	v_pk_mul_f32 v[56:57], v[56:57], s[2:3] op_sel_hi:[1,0]
	v_pk_mul_f32 v[50:51], v[50:51], s[2:3] op_sel_hi:[1,0]
	v_pk_mul_f32 v[52:53], v[52:53], s[2:3] op_sel_hi:[1,0]
	v_pk_mul_f32 v[46:47], v[46:47], s[2:3] op_sel_hi:[1,0]
	v_pk_mul_f32 v[48:49], v[48:49], s[2:3] op_sel_hi:[1,0]
	v_pk_mul_f32 v[42:43], v[42:43], s[2:3] op_sel_hi:[1,0]
	v_pk_mul_f32 v[44:45], v[44:45], s[2:3] op_sel_hi:[1,0]
	v_pk_mul_f32 v[38:39], v[38:39], s[2:3] op_sel_hi:[1,0]
	v_pk_mul_f32 v[40:41], v[40:41], s[2:3] op_sel_hi:[1,0]
	v_pk_mul_f32 v[34:35], v[34:35], s[2:3] op_sel_hi:[1,0]
	v_pk_mul_f32 v[36:37], v[36:37], s[2:3] op_sel_hi:[1,0]
	v_pk_mul_f32 v[30:31], v[30:31], s[2:3] op_sel_hi:[1,0]
	v_pk_mul_f32 v[32:33], v[32:33], s[2:3] op_sel_hi:[1,0]
	v_pk_mul_f32 v[26:27], v[26:27], s[2:3] op_sel_hi:[1,0]
	v_pk_mul_f32 v[28:29], v[28:29], s[2:3] op_sel_hi:[1,0]
	v_pk_mul_f32 v[22:23], v[22:23], s[2:3] op_sel_hi:[1,0]
	v_pk_mul_f32 v[24:25], v[24:25], s[2:3] op_sel_hi:[1,0]
	v_pk_mul_f32 v[18:19], v[18:19], s[2:3] op_sel_hi:[1,0]
	v_pk_mul_f32 v[20:21], v[20:21], s[2:3] op_sel_hi:[1,0]
	v_pk_mul_f32 v[14:15], v[14:15], s[2:3] op_sel_hi:[1,0]
	v_pk_mul_f32 v[16:17], v[16:17], s[2:3] op_sel_hi:[1,0]
	v_pk_mul_f32 v[10:11], v[10:11], s[2:3] op_sel_hi:[1,0]
	v_pk_mul_f32 v[12:13], v[12:13], s[2:3] op_sel_hi:[1,0]
	v_pk_mul_f32 v[6:7], v[6:7], s[2:3] op_sel_hi:[1,0]
	v_pk_mul_f32 v[8:9], v[8:9], s[2:3] op_sel_hi:[1,0]
	v_pk_mul_f32 v[2:3], v[2:3], s[2:3] op_sel_hi:[1,0]
	v_pk_mul_f32 v[4:5], v[4:5], s[2:3] op_sel_hi:[1,0]
	v_readlane_b32 s88, v254, 42
	v_readlane_b32 s89, v254, 43
	s_waitcnt vmcnt(7)
;     __device__ __forceinline__ bf16_t* G() const { return (bf16_t*)(ws + OFF_G); }
;     __device__ __forceinline__ bf16_t* Mb() const { return (bf16_t*)(ws + OFF_MB); }
; __device__ __forceinline__ unsigned pk2(float lo, float hi) { const f32x2_t f = {lo, hi}; const bf16x2_t b = __builtin_convertvector(f, bf16x2_t); return __builtin_bit_cast(unsigned, b); }
; #define LAS __attribute__((address_space(3)))
; __device__ __forceinline__ float ub(unsigned w, int j) { return (float)((w >> (8 * j)) & 0xffu); }
; template <bool PERMF = false, class F>
; __device__ __forceinline__ void epi_store_rows(LAS unsigned char* lds, int wid, int lane2, int fr, int fq, int wc, int mt, bf16_t* dbase, size_t dld, F getpk) {
;     LAS unsigned char* reg = lds + wid * 9216;
; #pragma unroll
;     for (int bj = 0; bj < 2; bj++)
; #pragma unroll
;         for (int n = 0; n < 2; n++)
; #pragma unroll
;             for (int m = 0; m < 4; m++) *(LAS u32x2*)(reg + ((bj * 2 + n) * 16 + fr) * LROW + (PERMF ? fq * 32 + m * 8 : fq * 8 + m * 32)) = getpk(bj, n, m);
; __device__ __forceinline__ void phase_gemm2(const Params& p, int layer, LAS unsigned char* lds) {
;     ...
;             epi_store_rows<true>(lds, wid, lane2, fr, fq, wc, mt, p.Mb() + f0, DM, [&](int bj, int n, int m) -> u32x2 {
;                 const int tk = mt * 256 + bj * 128 + wc * 32 + n * 16 + fr;
;                 const unsigned gw = *(const unsigned*)((const unsigned char*)p.G() + (size_t)tk * 3072 + 2048 + f0 + fq * 16 + m * 4);
;                 const f32x4 v = acc[ai][bj][m][n] * (1.f / 255.f);
;                 return (u32x2){pk2(v[0] * ub(gw, 0), v[1] * ub(gw, 1)), pk2(v[2] * ub(gw, 2), v[3] * ub(gw, 3))};
;             });
	v_cvt_f32_ubyte1_e32 v139, v192
	v_cvt_f32_ubyte0_e32 v138, v192
	v_pk_mul_f32 v[126:127], v[126:127], v[138:139]
	v_cvt_f32_ubyte3_e32 v139, v192
	v_cvt_f32_ubyte2_e32 v138, v192
	v_pk_mul_f32 v[128:129], v[128:129], v[138:139]
	v_cvt_pk_bf16_f32 v126, v126, v127
	v_cvt_pk_bf16_f32 v127, v128, v129
	v_cvt_f32_ubyte1_e32 v129, v193
	v_cvt_f32_ubyte0_e32 v128, v193
	v_pk_mul_f32 v[122:123], v[122:123], v[128:129]
	s_nop 0
	v_cvt_pk_bf16_f32 v128, v122, v123
	v_cvt_f32_ubyte3_e32 v123, v193
	v_cvt_f32_ubyte2_e32 v122, v193
	v_pk_mul_f32 v[122:123], v[124:125], v[122:123]
	s_nop 0
	v_cvt_pk_bf16_f32 v129, v122, v123
	v_cvt_f32_ubyte1_e32 v123, v194
	v_cvt_f32_ubyte0_e32 v122, v194
	v_pk_mul_f32 v[118:119], v[118:119], v[122:123]
	v_cvt_f32_ubyte3_e32 v123, v194
	v_cvt_f32_ubyte2_e32 v122, v194
	v_pk_mul_f32 v[120:121], v[120:121], v[122:123]
	v_cvt_pk_bf16_f32 v118, v118, v119
	v_cvt_pk_bf16_f32 v119, v120, v121
	v_cvt_f32_ubyte1_e32 v121, v195
	v_cvt_f32_ubyte0_e32 v120, v195
	v_pk_mul_f32 v[114:115], v[114:115], v[120:121]
	ds_write_b128 v155, v[126:129]
	v_cvt_pk_bf16_f32 v120, v114, v115
	v_cvt_f32_ubyte3_e32 v115, v195
	v_cvt_f32_ubyte2_e32 v114, v195
	v_pk_mul_f32 v[114:115], v[116:117], v[114:115]
	s_nop 0
	v_cvt_pk_bf16_f32 v121, v114, v115
	v_mad_i64_i32 v[114:115], s[6:7], v157, s90, v[152:153]
	v_lshl_add_u64 v[114:115], v[114:115], 0, s[4:5]
	v_lshl_add_u64 v[116:117], v[114:115], 0, v[0:1]
	v_lshl_add_u64 v[114:115], v[116:117], 0, s[8:9]
	v_add_co_u32_e32 v116, vcc, s81, v116
	ds_write_b128 v155, v[118:121] offset:16
	s_nop 0
	v_addc_co_u32_e32 v117, vcc, 0, v117, vcc
	s_waitcnt vmcnt(5)
	v_cvt_f32_ubyte1_e32 v121, v200
	v_cvt_f32_ubyte0_e32 v120, v200
	v_pk_mul_f32 v[110:111], v[110:111], v[120:121]
	v_cvt_f32_ubyte3_e32 v121, v200
	v_cvt_f32_ubyte2_e32 v120, v200
	v_pk_mul_f32 v[112:113], v[112:113], v[120:121]
	v_cvt_pk_bf16_f32 v110, v110, v111
	v_cvt_pk_bf16_f32 v111, v112, v113
	v_cvt_f32_ubyte1_e32 v113, v201
	v_cvt_f32_ubyte0_e32 v112, v201
	v_pk_mul_f32 v[106:107], v[106:107], v[112:113]
	s_nop 0
	v_cvt_pk_bf16_f32 v112, v106, v107
	v_cvt_f32_ubyte3_e32 v107, v201
	v_cvt_f32_ubyte2_e32 v106, v201
	v_pk_mul_f32 v[106:107], v[108:109], v[106:107]
	s_nop 0
	v_cvt_pk_bf16_f32 v113, v106, v107
	v_cvt_f32_ubyte1_e32 v107, v202
	v_cvt_f32_ubyte0_e32 v106, v202
	v_pk_mul_f32 v[102:103], v[102:103], v[106:107]
	v_cvt_f32_ubyte3_e32 v107, v202
	v_cvt_f32_ubyte2_e32 v106, v202
	v_pk_mul_f32 v[104:105], v[104:105], v[106:107]
	v_cvt_pk_bf16_f32 v102, v102, v103
	v_cvt_pk_bf16_f32 v103, v104, v105
	v_cvt_f32_ubyte1_e32 v105, v203
	v_cvt_f32_ubyte0_e32 v104, v203
	v_pk_mul_f32 v[98:99], v[98:99], v[104:105]
	ds_write_b128 v155, v[110:113] offset:2304
	v_cvt_pk_bf16_f32 v104, v98, v99
	v_cvt_f32_ubyte3_e32 v99, v203
	v_cvt_f32_ubyte2_e32 v98, v203
	v_pk_mul_f32 v[98:99], v[100:101], v[98:99]
	s_nop 0
	v_cvt_pk_bf16_f32 v105, v98, v99
	v_mad_i64_i32 v[98:99], s[6:7], v156, s90, v[152:153]
	v_lshl_add_u64 v[98:99], v[98:99], 0, s[4:5]
	v_lshl_add_u64 v[100:101], v[98:99], 0, v[0:1]
	v_lshl_add_u64 v[98:99], v[100:101], 0, s[8:9]
	v_add_co_u32_e32 v100, vcc, s81, v100
	ds_write_b128 v155, v[102:105] offset:2320
	s_nop 0
	v_addc_co_u32_e32 v101, vcc, 0, v101, vcc
	s_waitcnt vmcnt(3)
	v_cvt_f32_ubyte1_e32 v105, v208
	v_cvt_f32_ubyte0_e32 v104, v208
	v_pk_mul_f32 v[94:95], v[94:95], v[104:105]
	v_cvt_f32_ubyte3_e32 v105, v208
	v_cvt_f32_ubyte2_e32 v104, v208
	v_pk_mul_f32 v[96:97], v[96:97], v[104:105]
	v_cvt_pk_bf16_f32 v94, v94, v95
	v_cvt_pk_bf16_f32 v95, v96, v97
	v_cvt_f32_ubyte1_e32 v97, v209
	v_cvt_f32_ubyte0_e32 v96, v209
	v_pk_mul_f32 v[90:91], v[90:91], v[96:97]
	s_nop 0
	v_cvt_pk_bf16_f32 v96, v90, v91
	v_cvt_f32_ubyte3_e32 v91, v209
	v_cvt_f32_ubyte2_e32 v90, v209
	v_pk_mul_f32 v[90:91], v[92:93], v[90:91]
	s_nop 0
	v_cvt_pk_bf16_f32 v97, v90, v91
	v_cvt_f32_ubyte1_e32 v91, v210
	v_cvt_f32_ubyte0_e32 v90, v210
	v_pk_mul_f32 v[86:87], v[86:87], v[90:91]
	v_cvt_f32_ubyte3_e32 v91, v210
	v_cvt_f32_ubyte2_e32 v90, v210
	v_pk_mul_f32 v[88:89], v[88:89], v[90:91]
	v_cvt_pk_bf16_f32 v86, v86, v87
	v_cvt_pk_bf16_f32 v87, v88, v89
	v_cvt_f32_ubyte1_e32 v89, v211
	v_cvt_f32_ubyte0_e32 v88, v211
	v_pk_mul_f32 v[82:83], v[82:83], v[88:89]
	ds_write_b128 v155, v[94:97] offset:4608
	v_cvt_pk_bf16_f32 v88, v82, v83
	v_cvt_f32_ubyte3_e32 v83, v211
	v_cvt_f32_ubyte2_e32 v82, v211
	v_pk_mul_f32 v[82:83], v[84:85], v[82:83]
	s_nop 0
	v_cvt_pk_bf16_f32 v89, v82, v83
	v_mad_i64_i32 v[82:83], s[6:7], v149, s90, v[152:153]
	v_lshl_add_u64 v[82:83], v[82:83], 0, s[4:5]
	v_lshl_add_u64 v[82:83], v[82:83], 0, v[0:1]
	ds_write_b128 v155, v[86:89] offset:4624
	v_lshl_add_u64 v[86:87], v[82:83], 0, s[8:9]
	v_add_co_u32_e32 v82, vcc, s81, v82
	v_mov_b32_e32 v149, v1
	s_nop 0
	v_addc_co_u32_e32 v83, vcc, 0, v83, vcc
	s_waitcnt vmcnt(1)
	v_cvt_f32_ubyte1_e32 v89, v216
	v_cvt_f32_ubyte0_e32 v88, v216
	v_pk_mul_f32 v[78:79], v[78:79], v[88:89]
	v_cvt_f32_ubyte3_e32 v89, v216
	v_cvt_f32_ubyte2_e32 v88, v216
	v_pk_mul_f32 v[80:81], v[80:81], v[88:89]
	v_cvt_pk_bf16_f32 v78, v78, v79
	v_cvt_pk_bf16_f32 v79, v80, v81
	v_cvt_f32_ubyte1_e32 v81, v217
	v_cvt_f32_ubyte0_e32 v80, v217
	v_pk_mul_f32 v[74:75], v[74:75], v[80:81]
	v_lshl_add_u64 v[88:89], s[0:1], 0, v[148:149]
	v_cvt_pk_bf16_f32 v80, v74, v75
	v_cvt_f32_ubyte3_e32 v75, v217
	v_cvt_f32_ubyte2_e32 v74, v217
	v_pk_mul_f32 v[74:75], v[76:77], v[74:75]
	s_nop 0
	v_cvt_pk_bf16_f32 v81, v74, v75
	v_cvt_f32_ubyte1_e32 v75, v218
	v_cvt_f32_ubyte0_e32 v74, v218
	v_pk_mul_f32 v[70:71], v[70:71], v[74:75]
	v_cvt_f32_ubyte3_e32 v75, v218
	v_cvt_f32_ubyte2_e32 v74, v218
	v_pk_mul_f32 v[72:73], v[72:73], v[74:75]
	v_cvt_pk_bf16_f32 v70, v70, v71
	v_cvt_pk_bf16_f32 v71, v72, v73
	v_cvt_f32_ubyte1_e32 v73, v219
	v_cvt_f32_ubyte0_e32 v72, v219
	v_pk_mul_f32 v[66:67], v[66:67], v[72:73]
	ds_write_b128 v155, v[78:81] offset:6912
	v_cvt_pk_bf16_f32 v72, v66, v67
	v_cvt_f32_ubyte3_e32 v67, v219
	v_cvt_f32_ubyte2_e32 v66, v219
	v_pk_mul_f32 v[66:67], v[68:69], v[66:67]
	s_nop 0
	v_cvt_pk_bf16_f32 v73, v66, v67
	ds_write_b128 v155, v[70:73] offset:6928
	ds_read_b128 v[68:71], v154
	v_lshl_add_u64 v[66:67], v[88:89], 0, v[146:147]
	s_waitcnt lgkmcnt(0)
;     __device__ __forceinline__ bf16_t* G() const { return (bf16_t*)(ws + OFF_G); }
;     __device__ __forceinline__ bf16_t* Mb() const { return (bf16_t*)(ws + OFF_MB); }
; __device__ __forceinline__ unsigned pk2(float lo, float hi) { const f32x2_t f = {lo, hi}; const bf16x2_t b = __builtin_convertvector(f, bf16x2_t); return __builtin_bit_cast(unsigned, b); }
; #define LAS __attribute__((address_space(3)))
; __device__ __forceinline__ float ub(unsigned w, int j) { return (float)((w >> (8 * j)) & 0xffu); }
; template <bool PERMF = false, class F>
; __device__ __forceinline__ void epi_store_rows(LAS unsigned char* lds, int wid, int lane2, int fr, int fq, int wc, int mt, bf16_t* dbase, size_t dld, F getpk) {
;     ...
; #pragma unroll
;     for (int i = 0; i < 8; i++) {
;         const int c = lane2 + 64 * i, row = c >> 3, ch = c & 7;
;         const u32x4 w = *(const LAS u32x4*)(reg + row * LROW + ch * 16);
;         const int tk2 = mt * 256 + (row >> 5) * 128 + wc * 32 + (row & 31);
;         if (PERMF) *(u32x4*)(dbase + (size_t)tk2 * dld + ch * 8) = w;
;         else __builtin_nontemporal_store(w, (u32x4*)(dbase + (size_t)tk2 * dld + ch * 8));
;     }
; __device__ __forceinline__ void phase_gemm2(const Params& p, int layer, LAS unsigned char* lds) {
;     ...
;             epi_store_rows<true>(lds, wid, lane2, fr, fq, wc, mt, p.Mb() + f0, DM, [&](int bj, int n, int m) -> u32x2 {
;                 const int tk = mt * 256 + bj * 128 + wc * 32 + n * 16 + fr;
;                 const unsigned gw = *(const unsigned*)((const unsigned char*)p.G() + (size_t)tk * 3072 + 2048 + f0 + fq * 16 + m * 4);
;                 const f32x4 v = acc[ai][bj][m][n] * (1.f / 255.f);
;                 return (u32x2){pk2(v[0] * ub(gw, 0), v[1] * ub(gw, 1)), pk2(v[2] * ub(gw, 2), v[3] * ub(gw, 3))};
;             });
	s_waitcnt vmcnt(0)
	global_store_dwordx4 v[66:67], v[68:71], off
	ds_read_b128 v[70:73], v154 offset:1152
	s_nop 0
	v_lshl_add_u64 v[68:69], v[88:89], 0, v[144:145]
	s_waitcnt lgkmcnt(0)
	global_store_dwordx4 v[68:69], v[70:73], off
	ds_read_b128 v[72:75], v154 offset:2304
	s_nop 0
	v_lshl_add_u64 v[70:71], v[88:89], 0, v[142:143]
	s_waitcnt lgkmcnt(0)
	global_store_dwordx4 v[70:71], v[72:75], off
	ds_read_b128 v[74:77], v154 offset:3456
	s_nop 0
	v_lshl_add_u64 v[72:73], v[88:89], 0, v[140:141]
	s_waitcnt lgkmcnt(0)
	global_store_dwordx4 v[72:73], v[74:77], off
	ds_read_b128 v[76:79], v154 offset:4608
	s_nop 0
	v_lshl_add_u64 v[74:75], v[88:89], 0, v[136:137]
	s_waitcnt lgkmcnt(0)
	global_store_dwordx4 v[74:75], v[76:79], off
	ds_read_b128 v[78:81], v154 offset:5760
	s_nop 0
	v_lshl_add_u64 v[76:77], v[88:89], 0, v[134:135]
	s_waitcnt lgkmcnt(0)
	global_store_dwordx4 v[76:77], v[78:81], off
	ds_read_b128 v[80:83], v154 offset:6912
	s_nop 0
	v_lshl_add_u64 v[78:79], v[88:89], 0, v[132:133]
	s_waitcnt lgkmcnt(0)
	global_store_dwordx4 v[78:79], v[80:83], off
	ds_read_b128 v[82:85], v154 offset:8064
	s_nop 0
	v_lshl_add_u64 v[80:81], v[88:89], 0, v[130:131]
	s_waitcnt lgkmcnt(0)
	global_store_dwordx4 v[80:81], v[82:85], off
	v_cvt_f32_ubyte1_e32 v89, v196
	v_cvt_f32_ubyte0_e32 v88, v196
	v_pk_mul_f32 v[62:63], v[62:63], v[88:89]
	v_cvt_f32_ubyte3_e32 v89, v196
	v_cvt_f32_ubyte2_e32 v88, v196
	v_pk_mul_f32 v[64:65], v[64:65], v[88:89]
	v_cvt_pk_bf16_f32 v62, v62, v63
	v_cvt_pk_bf16_f32 v63, v64, v65
	v_cvt_f32_ubyte1_e32 v65, v197
	v_cvt_f32_ubyte0_e32 v64, v197
	v_pk_mul_f32 v[58:59], v[58:59], v[64:65]
	s_nop 0
	v_cvt_pk_bf16_f32 v64, v58, v59
	v_cvt_f32_ubyte3_e32 v59, v197
	v_cvt_f32_ubyte2_e32 v58, v197
	v_pk_mul_f32 v[58:59], v[60:61], v[58:59]
	s_nop 0
	v_cvt_pk_bf16_f32 v65, v58, v59
	v_cvt_f32_ubyte1_e32 v59, v198
	v_cvt_f32_ubyte0_e32 v58, v198
	v_pk_mul_f32 v[54:55], v[54:55], v[58:59]
	v_cvt_f32_ubyte3_e32 v59, v198
	v_cvt_f32_ubyte2_e32 v58, v198
	v_pk_mul_f32 v[56:57], v[56:57], v[58:59]
	v_cvt_pk_bf16_f32 v54, v54, v55
	v_cvt_pk_bf16_f32 v55, v56, v57
	v_cvt_f32_ubyte1_e32 v57, v199
	v_cvt_f32_ubyte0_e32 v56, v199
	v_pk_mul_f32 v[50:51], v[50:51], v[56:57]
	ds_write_b128 v155, v[62:65]
	v_cvt_pk_bf16_f32 v56, v50, v51
	v_cvt_f32_ubyte3_e32 v51, v199
	v_cvt_f32_ubyte2_e32 v50, v199
	v_pk_mul_f32 v[50:51], v[52:53], v[50:51]
	s_nop 0
	v_cvt_pk_bf16_f32 v57, v50, v51
	ds_write_b128 v155, v[54:57] offset:16
	v_cvt_f32_ubyte1_e32 v55, v204
	v_cvt_f32_ubyte0_e32 v54, v204
	v_pk_mul_f32 v[46:47], v[46:47], v[54:55]
	v_cvt_f32_ubyte3_e32 v55, v204
	v_cvt_f32_ubyte2_e32 v54, v204
	v_pk_mul_f32 v[48:49], v[48:49], v[54:55]
	v_cvt_pk_bf16_f32 v46, v46, v47
	v_cvt_pk_bf16_f32 v47, v48, v49
	v_cvt_f32_ubyte1_e32 v49, v205
	v_cvt_f32_ubyte0_e32 v48, v205
	v_pk_mul_f32 v[42:43], v[42:43], v[48:49]
	s_nop 0
	v_cvt_pk_bf16_f32 v48, v42, v43
	v_cvt_f32_ubyte3_e32 v43, v205
	v_cvt_f32_ubyte2_e32 v42, v205
	v_pk_mul_f32 v[42:43], v[44:45], v[42:43]
	s_nop 0
	v_cvt_pk_bf16_f32 v49, v42, v43
	v_cvt_f32_ubyte1_e32 v43, v206
	v_cvt_f32_ubyte0_e32 v42, v206
	v_pk_mul_f32 v[38:39], v[38:39], v[42:43]
	v_cvt_f32_ubyte3_e32 v43, v206
	v_cvt_f32_ubyte2_e32 v42, v206
	v_pk_mul_f32 v[40:41], v[40:41], v[42:43]
	v_cvt_pk_bf16_f32 v38, v38, v39
	v_cvt_pk_bf16_f32 v39, v40, v41
	v_cvt_f32_ubyte1_e32 v41, v207
	v_cvt_f32_ubyte0_e32 v40, v207
	v_pk_mul_f32 v[34:35], v[34:35], v[40:41]
	ds_write_b128 v155, v[46:49] offset:2304
	v_cvt_pk_bf16_f32 v40, v34, v35
	v_cvt_f32_ubyte3_e32 v35, v207
	v_cvt_f32_ubyte2_e32 v34, v207
	v_pk_mul_f32 v[34:35], v[36:37], v[34:35]
	s_nop 0
	v_cvt_pk_bf16_f32 v41, v34, v35
	ds_write_b128 v155, v[38:41] offset:2320
	v_cvt_f32_ubyte1_e32 v39, v212
	v_cvt_f32_ubyte0_e32 v38, v212
	v_pk_mul_f32 v[30:31], v[30:31], v[38:39]
	v_cvt_f32_ubyte3_e32 v39, v212
	v_cvt_f32_ubyte2_e32 v38, v212
	v_pk_mul_f32 v[32:33], v[32:33], v[38:39]
	v_cvt_pk_bf16_f32 v30, v30, v31
	v_cvt_pk_bf16_f32 v31, v32, v33
	v_cvt_f32_ubyte1_e32 v33, v213
	v_cvt_f32_ubyte0_e32 v32, v213
	v_pk_mul_f32 v[26:27], v[26:27], v[32:33]
	s_nop 0
	v_cvt_pk_bf16_f32 v32, v26, v27
	v_cvt_f32_ubyte3_e32 v27, v213
	v_cvt_f32_ubyte2_e32 v26, v213
	v_pk_mul_f32 v[26:27], v[28:29], v[26:27]
	s_nop 0
	v_cvt_pk_bf16_f32 v33, v26, v27
	v_cvt_f32_ubyte1_e32 v27, v214
	v_cvt_f32_ubyte0_e32 v26, v214
	v_pk_mul_f32 v[22:23], v[22:23], v[26:27]
	v_cvt_f32_ubyte3_e32 v27, v214
	v_cvt_f32_ubyte2_e32 v26, v214
	v_pk_mul_f32 v[24:25], v[24:25], v[26:27]
	v_cvt_pk_bf16_f32 v22, v22, v23
	v_cvt_pk_bf16_f32 v23, v24, v25
	v_cvt_f32_ubyte1_e32 v25, v215
	v_cvt_f32_ubyte0_e32 v24, v215
	v_pk_mul_f32 v[18:19], v[18:19], v[24:25]
	ds_write_b128 v155, v[30:33] offset:4608
	v_cvt_pk_bf16_f32 v24, v18, v19
	v_cvt_f32_ubyte3_e32 v19, v215
	v_cvt_f32_ubyte2_e32 v18, v215
	v_pk_mul_f32 v[18:19], v[20:21], v[18:19]
	s_nop 0
	v_cvt_pk_bf16_f32 v25, v18, v19
	ds_write_b128 v155, v[22:25] offset:4624
	v_cvt_f32_ubyte1_e32 v23, v220
	v_cvt_f32_ubyte0_e32 v22, v220
	v_pk_mul_f32 v[14:15], v[14:15], v[22:23]
	v_cvt_f32_ubyte3_e32 v23, v220
	v_cvt_f32_ubyte2_e32 v22, v220
	v_pk_mul_f32 v[16:17], v[16:17], v[22:23]
	v_cvt_pk_bf16_f32 v14, v14, v15
	v_cvt_pk_bf16_f32 v15, v16, v17
	v_cvt_f32_ubyte1_e32 v17, v221
	v_cvt_f32_ubyte0_e32 v16, v221
	v_pk_mul_f32 v[10:11], v[10:11], v[16:17]
	s_nop 0
	v_cvt_pk_bf16_f32 v16, v10, v11
	v_cvt_f32_ubyte3_e32 v11, v221
	v_cvt_f32_ubyte2_e32 v10, v221
	v_pk_mul_f32 v[10:11], v[12:13], v[10:11]
	s_nop 0
	v_cvt_pk_bf16_f32 v17, v10, v11
	v_cvt_f32_ubyte1_e32 v11, v222
	v_cvt_f32_ubyte0_e32 v10, v222
	v_pk_mul_f32 v[6:7], v[6:7], v[10:11]
	v_cvt_f32_ubyte3_e32 v11, v222
	v_cvt_f32_ubyte2_e32 v10, v222
	v_pk_mul_f32 v[8:9], v[8:9], v[10:11]
	v_cvt_pk_bf16_f32 v6, v6, v7
	v_cvt_pk_bf16_f32 v7, v8, v9
	v_cvt_f32_ubyte1_e32 v9, v223
	v_cvt_f32_ubyte0_e32 v8, v223
	v_pk_mul_f32 v[2:3], v[2:3], v[8:9]
	ds_write_b128 v155, v[14:17] offset:6912
	v_cvt_pk_bf16_f32 v8, v2, v3
	v_cvt_f32_ubyte3_e32 v3, v223
	v_cvt_f32_ubyte2_e32 v2, v223
	v_pk_mul_f32 v[2:3], v[4:5], v[2:3]
	s_nop 0
	v_cvt_pk_bf16_f32 v9, v2, v3
	ds_write_b128 v155, v[6:9] offset:6928
	ds_read_b128 v[2:5], v154
	s_waitcnt lgkmcnt(0)
;     __device__ __forceinline__ unsigned* BAR() const { return (unsigned*)(ws + OFF_BAR); }
; #define LAS __attribute__((address_space(3)))
; __device__ __forceinline__ unsigned xb_add(unsigned* p, unsigned v) { return __hip_atomic_fetch_add(p, v, __ATOMIC_RELAXED, __HIP_MEMORY_SCOPE_AGENT); }
; #define BAR __builtin_amdgcn_s_barrier()
; template <bool PERMF = false, class F>
; __device__ __forceinline__ void epi_store_rows(LAS unsigned char* lds, int wid, int lane2, int fr, int fq, int wc, int mt, bf16_t* dbase, size_t dld, F getpk) {
;     ...
; #pragma unroll
;     for (int i = 0; i < 8; i++) {
;         const int c = lane2 + 64 * i, row = c >> 3, ch = c & 7;
;         const u32x4 w = *(const LAS u32x4*)(reg + row * LROW + ch * 16);
;         const int tk2 = mt * 256 + (row >> 5) * 128 + wc * 32 + (row & 31);
;         if (PERMF) *(u32x4*)(dbase + (size_t)tk2 * dld + ch * 8) = w;
;         else __builtin_nontemporal_store(w, (u32x4*)(dbase + (size_t)tk2 * dld + ch * 8));
;     }
; __device__ __forceinline__ void phase_gemm2(const Params& p, int layer, LAS unsigned char* lds) {
;     ...
;         asm volatile("s_waitcnt vmcnt(0)" ::: "memory");
;         __syncthreads();
;         if (threadIdx.x == 0) {
;             __builtin_amdgcn_fence(__ATOMIC_RELEASE, "agent");
;             asm volatile("s_waitcnt vmcnt(0)" ::: "memory");
;             xb_add(&p.BAR()[G23_PC(mt)], 1u);
;         }
	global_store_dwordx4 v[66:67], v[2:5], off offset:256
	ds_read_b128 v[2:5], v154 offset:1152
	s_waitcnt lgkmcnt(0)
	global_store_dwordx4 v[68:69], v[2:5], off offset:256
	ds_read_b128 v[2:5], v154 offset:2304
	s_waitcnt lgkmcnt(0)
	global_store_dwordx4 v[70:71], v[2:5], off offset:256
	ds_read_b128 v[2:5], v154 offset:3456
	s_waitcnt lgkmcnt(0)
	global_store_dwordx4 v[72:73], v[2:5], off offset:256
	ds_read_b128 v[2:5], v154 offset:4608
	s_waitcnt lgkmcnt(0)
	global_store_dwordx4 v[74:75], v[2:5], off offset:256
	ds_read_b128 v[2:5], v154 offset:5760
	s_waitcnt lgkmcnt(0)
	global_store_dwordx4 v[76:77], v[2:5], off offset:256
	ds_read_b128 v[2:5], v154 offset:6912
	s_waitcnt lgkmcnt(0)
	global_store_dwordx4 v[78:79], v[2:5], off offset:256
	ds_read_b128 v[2:5], v154 offset:8064
	s_waitcnt lgkmcnt(0)
	global_store_dwordx4 v[80:81], v[2:5], off offset:256
	s_waitcnt vmcnt(0)
	s_barrier
	s_and_saveexec_b64 s[0:1], s[88:89]
	s_cbranch_execz .LBB0_564
	s_mov_b64 s[4:5], exec
	v_mbcnt_lo_u32_b32 v0, s4, 0
	buffer_wbl2 sc1
	s_waitcnt vmcnt(0)
	s_waitcnt vmcnt(0)
	v_mbcnt_hi_u32_b32 v0, s5, v0
	v_cmp_eq_u32_e32 vcc, 0, v0
	s_and_b64 s[6:7], exec, vcc
	s_mov_b64 exec, s[6:7]
	s_cbranch_execz .LBB0_564
	s_lshl_b32 s6, s66, 6
	s_ashr_i32 s7, s6, 31
	s_lshl_b64 s[6:7], s[6:7], 2
	s_add_u32 s6, s20, s6
	s_addc_u32 s7, s21, s7
	s_bcnt1_i32_b64 s4, s[4:5]
	v_mov_b32_e32 v0, s4
	global_atomic_add v176, v0, s[6:7] offset:1792
	s_branch .LBB0_564
